# DSA batch loop: LDS parking addresses and the xor-32 exchange address kept in registers for the item instead of recomputed per batch
# baseline (speedup 1.0000x reference)
; #define LAS __attribute__((address_space(3)))
;     ...
;     { const int c16 = lane & 15, quad = lane >> 4;
;       typedef unsigned short u16x4 __attribute__((ext_vector_type(4)));
;       bf16x8 qa[4];
;       { const u16* qp = prow + qgrow * NP + C_QL + (c16 & 3) * 128 + quad * 8;
; #pragma unroll
;         for (int ks = 0; ks < 4; ++ks) qa[ks] = *(const bf16x8*)(qp + ks * 32); }
;       f32x4 oacc[8];
; #pragma unroll
;       for (int c = 0; c < 8; ++c) oacc[c] = (f32x4){0.f, 0.f, 0.f, 0.f};
;       const unsigned fsw = ((c16 & 3) << 2) | (c16 >> 2);
;       const unsigned wb = (unsigned)(unsigned long long)wbase;
;       unsigned tra[8][2];
;       { const unsigned q4 = c16 >> 2, p4 = c16 & 3;
; #pragma unroll
;         for (int t = 0; t < 2; ++t) { const unsigned fv = (q4 << 2) | ((2 * quad + t) & 3), rowb = wb + (8 * quad + 4 * t + q4) * 256 + 8 * (p4 & 1);
; #pragma unroll
;             for (int c = 0; c < 8; ++c) tra[c][t] = rowb + 16 * ((2 * c + (p4 >> 1)) ^ fv); } }
;       LAS u16* pbT = (LAS u16*)pbuf;
;       float mrun = -1e30f, lsum = 0.f;
;       const int nb = (sm & 8) ? ((kcount + 63) >> 6) : 0;
;       u32x4 w[4][4];
;       auto gl = [&](int b) {
; #pragma unroll
;           for (int jj = 0; jj < 4; ++jj) { const int kx = list[(b * 4 + jj) * 16 + c16] & 4095; const u16* cp = prow + (size_t)kx * NP + C_BC + quad * 8;
; #pragma unroll
;               for (int ks = 0; ks < 4; ++ks) w[jj][ks] = *(const u32x4*)(cp + ks * 32); } };
;       if (nb > 0) gl(0);
.LBB0_926:
	v_lshrrev_b32_e32 v128, 4, v163
	v_and_b32_e32 v127, 15, v174
	v_lshlrev_b32_e32 v18, 3, v128
	v_mov_b32_e32 v109, 0
	s_andn2_b64 vcc, exec, s[0:1]
	v_and_b32_e32 v126, 48, v174
	v_lshlrev_b32_e32 v124, 1, v18
	v_cmp_eq_u32_e64 s[38:39], 0, v127
	v_lshl_add_u32 v129, v128, 2, s56
	v_mov_b32_e32 v108, v109
	v_mov_b32_e32 v107, v109
	v_mov_b32_e32 v106, v109
	v_mov_b32_e32 v113, v109
	v_mov_b32_e32 v112, v109
	v_mov_b32_e32 v111, v109
	v_mov_b32_e32 v110, v109
	v_mov_b32_e32 v93, v109
	v_mov_b32_e32 v92, v109
	v_mov_b32_e32 v91, v109
	v_mov_b32_e32 v90, v109
	v_mov_b32_e32 v85, v109
	v_mov_b32_e32 v84, v109
	v_mov_b32_e32 v83, v109
	v_mov_b32_e32 v82, v109
	v_mov_b32_e32 v89, v109
	v_mov_b32_e32 v88, v109
	v_mov_b32_e32 v87, v109
	v_mov_b32_e32 v86, v109
	v_mov_b32_e32 v97, v109
	v_mov_b32_e32 v96, v109
	v_mov_b32_e32 v95, v109
	v_mov_b32_e32 v94, v109
	v_mov_b32_e32 v105, v109
	v_mov_b32_e32 v104, v109
	v_mov_b32_e32 v103, v109
	v_mov_b32_e32 v102, v109
	v_mov_b32_e32 v101, v109
	v_mov_b32_e32 v100, v109
	v_mov_b32_e32 v99, v109
	v_mov_b32_e32 v98, v109
	v_mov_b32_e32 v118, v109
	s_cbranch_vccnz .LBB0_953
	s_mul_hi_i32 s1, s61, 0x5800
	s_mulk_i32 s61, 0x5800
	v_lshlrev_b32_e32 v0, 7, v127
	s_add_u32 s0, s54, s61
	v_and_b32_e32 v82, 0x180, v0
	s_addc_u32 s1, s55, s1
	v_lshlrev_b32_e32 v0, 1, v82
	v_lshl_add_u64 v[2:3], s[0:1], 0, v[0:1]
	v_lshrrev_b32_e32 v83, 2, v127
	v_lshlrev_b32_e32 v0, 1, v128
	v_and_b32_e32 v84, 12, v174
	v_and_b32_e32 v85, 2, v0
	v_or_b32_e32 v0, v18, v83
	v_lshlrev_b32_e32 v18, 3, v127
	v_or_b32_e32 v86, v85, v84
	v_bfe_u32 v19, v174, 1, 1
	v_and_or_b32 v18, v18, 8, s60
	v_mov_b32_e32 v125, v1
	v_lshl_add_u32 v88, v0, 8, v18
	v_or_b32_e32 v0, v86, v19
	v_or_b32_e32 v89, 2, v19
	v_lshlrev_b32_e32 v95, 1, v127
	v_lshl_add_u64 v[14:15], v[2:3], 0, v[124:125]
	v_lshl_add_u32 v130, v0, 4, v88
	v_bitop3_b32 v0, v85, v89, v84 bitop3:0x36
	v_or_b32_e32 v90, 4, v19
	v_add_u32_e32 v96, s56, v95
	global_load_dwordx4 v[2:5], v[14:15], off offset:3072
	global_load_dwordx4 v[6:9], v[14:15], off offset:3136
	global_load_dwordx4 v[10:13], v[14:15], off offset:3200
	s_nop 0
	global_load_dwordx4 v[14:17], v[14:15], off offset:3264
	v_lshl_add_u32 v131, v0, 4, v88
	v_bitop3_b32 v0, v85, v90, v84 bitop3:0x36
	v_or_b32_e32 v91, 6, v19
	ds_read_u16 v18, v96
	ds_read_u16 v20, v96 offset:32
	v_lshl_add_u32 v132, v0, 4, v88
	v_bitop3_b32 v0, v85, v91, v84 bitop3:0x36
	v_or_b32_e32 v92, 8, v19
	v_lshl_add_u32 v133, v0, 4, v88
	v_bitop3_b32 v0, v85, v92, v84 bitop3:0x36
	v_or_b32_e32 v93, 10, v19
	v_lshl_add_u32 v134, v0, 4, v88
	v_bitop3_b32 v0, v85, v93, v84 bitop3:0x36
	v_or_b32_e32 v94, 12, v19
	v_lshl_add_u32 v135, v0, 4, v88
	v_bitop3_b32 v0, v85, v94, v84 bitop3:0x36
	ds_read_u16 v50, v96 offset:64
	ds_read_u16 v51, v96 offset:96
	s_mov_b32 s1, 0x5040100
	v_lshl_add_u32 v136, v0, 4, v88
	s_waitcnt lgkmcnt(2)
	v_perm_b32 v0, v20, v18, s1
	s_movk_i32 s20, 0xfff
	v_and_b32_e32 v18, 0xfff0fff, v0
	v_bitop3_b32 v0, v0, s20, v207 bitop3:0x80
	v_mul_u32_u24_e32 v0, 0x5800, v0
	v_or_b32_e32 v97, 14, v19
	v_mul_u32_u24_sdwa v34, v18, s33 dst_sel:DWORD dst_unused:UNUSED_PAD src0_sel:WORD_1 src1_sel:DWORD
	v_lshl_add_u64 v[18:19], s[54:55], 0, v[0:1]
	v_lshl_add_u64 v[18:19], v[18:19], 0, v[124:125]
	s_movk_i32 s0, 0x1000
	v_mov_b32_e32 v35, v1
	s_waitcnt lgkmcnt(0)
	v_perm_b32 v0, v51, v50, s1
	v_add_co_u32_e32 v26, vcc, s0, v18
	v_lshl_add_u64 v[34:35], s[54:55], 0, v[34:35]
	v_and_b32_e32 v50, 0xfff0fff, v0
	v_bitop3_b32 v0, v0, s20, v207 bitop3:0x80
	v_addc_co_u32_e32 v27, vcc, 0, v19, vcc
	v_lshl_add_u64 v[34:35], v[34:35], 0, v[124:125]
	v_mul_u32_u24_e32 v0, 0x5800, v0
	v_add_co_u32_e32 v42, vcc, s0, v34
	v_mul_u32_u24_sdwa v66, v50, s33 dst_sel:DWORD dst_unused:UNUSED_PAD src0_sel:WORD_1 src1_sel:DWORD
	v_lshl_add_u64 v[50:51], s[54:55], 0, v[0:1]
	v_addc_co_u32_e32 v43, vcc, 0, v35, vcc
	v_lshl_add_u64 v[50:51], v[50:51], 0, v[124:125]
	v_mov_b32_e32 v67, v1
	v_add_co_u32_e32 v58, vcc, s0, v50
	v_lshl_add_u64 v[66:67], s[54:55], 0, v[66:67]
	s_nop 0
	v_addc_co_u32_e32 v59, vcc, 0, v51, vcc
	v_lshl_add_u64 v[66:67], v[66:67], 0, v[124:125]
	s_mov_b64 s[24:25], 0x1000
	v_add_co_u32_e32 v74, vcc, s0, v66
	v_lshl_add_u64 v[30:31], v[18:19], 0, s[24:25]
	v_lshl_add_u64 v[46:47], v[34:35], 0, s[24:25]
	v_lshl_add_u64 v[62:63], v[50:51], 0, s[24:25]
	v_lshl_add_u64 v[78:79], v[66:67], 0, s[24:25]
	v_addc_co_u32_e32 v75, vcc, 0, v67, vcc
	global_load_dwordx4 v[18:21], v[30:31], off offset:64
	global_load_dwordx4 v[22:25], v[30:31], off offset:128
	s_nop 0
	global_load_dwordx4 v[26:29], v[26:27], off
	s_nop 0
	global_load_dwordx4 v[30:33], v[30:31], off offset:192
	s_nop 0
	global_load_dwordx4 v[34:37], v[46:47], off offset:64
	global_load_dwordx4 v[38:41], v[46:47], off offset:128
	s_nop 0
	global_load_dwordx4 v[42:45], v[42:43], off
	s_nop 0
	global_load_dwordx4 v[46:49], v[46:47], off offset:192
	s_nop 0
	global_load_dwordx4 v[50:53], v[62:63], off offset:64
	global_load_dwordx4 v[54:57], v[62:63], off offset:128
	s_nop 0
	global_load_dwordx4 v[58:61], v[58:59], off
	s_nop 0
	global_load_dwordx4 v[62:65], v[62:63], off offset:192
	s_nop 0
	global_load_dwordx4 v[66:69], v[78:79], off offset:64
	global_load_dwordx4 v[70:73], v[78:79], off offset:128
	s_nop 0
	global_load_dwordx4 v[74:77], v[74:75], off
	s_nop 0
	global_load_dwordx4 v[78:81], v[78:79], off offset:192
	v_lshrrev_b32_e32 v87, 1, v174
	v_bitop3_b32 v0, v85, v97, v84 bitop3:0x36
	v_lshl_add_u32 v137, v0, 4, v88
	v_add_u32_e32 v0, 0x400, v88
	v_bitop3_b32 v84, v86, v87, 1 bitop3:0x72
	v_lshl_add_u32 v138, v84, 4, v0
	v_bitop3_b32 v84, v86, v89, 1 bitop3:0x36
; #define LAS __attribute__((address_space(3)))
;     ...
;       const unsigned fsw = ((c16 & 3) << 2) | (c16 >> 2);
;       const unsigned wb = (unsigned)(unsigned long long)wbase;
;       unsigned tra[8][2];
;       { const unsigned q4 = c16 >> 2, p4 = c16 & 3;
; #pragma unroll
;         for (int t = 0; t < 2; ++t) { const unsigned fv = (q4 << 2) | ((2 * quad + t) & 3), rowb = wb + (8 * quad + 4 * t + q4) * 256 + 8 * (p4 & 1);
; #pragma unroll
;             for (int c = 0; c < 8; ++c) tra[c][t] = rowb + 16 * ((2 * c + (p4 >> 1)) ^ fv); } }
;     ...
;           for (int jj = 0; jj < 4; ++jj) {
;               const int rho = jj * 16 + c16, slot = b * 64 + rho;
;               f32x4 a = {0.f, 0.f, 0.f, 0.f}; float ss = 0.f;
; #pragma unroll
;               for (int ks = 0; ks < 4; ++ks) {
; #pragma unroll
;                   for (int e = 0; e < 4; ++e) asm("v_dot2_f32_bf16 %0, %1, %1, %0" : "+v"(ss) : "v"(w[jj][ks][e]));
;                   a = __builtin_amdgcn_mfma_f32_16x16x32_bf16(qa[ks], *reinterpret_cast<const bf16x8*>(&w[jj][ks]), a, 0, 0, 0);
;                   *(LAS u32x4*)(wbase + rho * 256 + (((ks * 4 + quad) ^ fsw) << 4)) = w[jj][ks]; }
;               ss += __shfl_xor(ss, 16); ss += __shfl_xor(ss, 32);
;               const float rstd = rsqrtf(ss * (1.f / 128.f) + EPS);
;               const float av = quad == 0 ? a[0] : (quad == 1 ? a[1] : (quad == 2 ? a[2] : a[3]));
;               rsv[jj] = rstd; lgv[jj] = (slot < kcount) ? av * rstd * 0.08838834764831845f : -__builtin_inff();
;           }
	v_lshl_add_u32 v139, v84, 4, v0
	v_bitop3_b32 v84, v86, v90, 1 bitop3:0x36
	v_lshl_add_u32 v140, v84, 4, v0
	v_bitop3_b32 v84, v86, v91, 1 bitop3:0x36
	v_lshl_add_u32 v141, v84, 4, v0
	v_bitop3_b32 v84, v86, v92, 1 bitop3:0x36
	v_lshl_add_u32 v142, v84, 4, v0
	v_bitop3_b32 v84, v86, v93, 1 bitop3:0x36
	v_lshl_add_u32 v143, v84, 4, v0
	v_bitop3_b32 v84, v86, v94, 1 bitop3:0x36
	v_lshl_add_u32 v144, v84, 4, v0
	v_bitop3_b32 v84, v86, v97, 1 bitop3:0x36
	v_lshl_add_u32 v145, v84, 4, v0
	v_lshlrev_b32_e32 v0, 2, v127
	v_and_b32_e32 v0, 12, v0
	v_bitop3_b32 v85, v0, v128, v83 bitop3:0x36
	v_lshlrev_b32_e32 v147, 4, v85
	v_or_b32_e32 v85, 4, v128
	v_bitop3_b32 v85, v0, v85, v83 bitop3:0x36
	v_lshlrev_b32_e32 v148, 4, v85
	v_or_b32_e32 v85, 8, v128
	v_bitop3_b32 v85, v0, v85, v83 bitop3:0x36
	v_lshlrev_b32_e32 v149, 4, v85
	v_or_b32_e32 v85, 12, v128
	v_lshlrev_b32_e32 v84, 7, v128
	v_add_u32_e32 v82, s56, v82
	v_lshl_add_u32 v146, v127, 8, s60
	v_bitop3_b32 v0, v0, v85, v83 bitop3:0x36
	s_add_i32 s57, s57, 0x20080
	v_mov_b32_e32 v159, 0
	s_mov_b32 s24, 0
	v_cmp_eq_u32_e64 s[40:41], 2, v128
	v_cmp_eq_u32_e64 s[66:67], 1, v128
	v_cmp_eq_u32_e64 s[68:69], 3, v128
	v_lshlrev_b32_e32 v150, 4, v0
	v_add_u32_e32 v151, 0x1000, v146
	v_add_u32_e32 v152, 0x2000, v146
	v_add_u32_e32 v153, 0x3000, v146
	v_add_u32_e32 v244, v146, v147
	v_add_u32_e32 v245, v146, v148
	v_add_u32_e32 v246, v146, v149
	v_add_u32_e32 v247, v146, v150
	v_xor_b32_e32 v248, 32, v206
	v_lshlrev_b32_e32 v248, 2, v248
	v_add_u32_e32 v154, s57, v95
	v_mov_b32_e32 v160, 0xf149f2ca
	v_add_u32_e32 v155, v96, v84
	v_add_u32_e32 v156, v82, v126
	v_mov_b32_e32 v157, v127
	v_mov_b32_e32 v98, 0
	v_mov_b32_e32 v99, v159
	v_mov_b32_e32 v100, v159
	v_mov_b32_e32 v101, v159
	v_mov_b32_e32 v102, 0
	v_mov_b32_e32 v103, v159
	v_mov_b32_e32 v104, v159
	v_mov_b32_e32 v105, v159
	v_mov_b32_e32 v94, 0
	v_mov_b32_e32 v95, v159
	v_mov_b32_e32 v96, v159
	v_mov_b32_e32 v97, v159
	v_mov_b32_e32 v86, 0
	v_mov_b32_e32 v87, v159
	v_mov_b32_e32 v88, v159
	v_mov_b32_e32 v89, v159
	v_mov_b32_e32 v82, 0
	v_mov_b32_e32 v83, v159
	v_mov_b32_e32 v84, v159
	v_mov_b32_e32 v85, v159
	v_mov_b32_e32 v90, 0
	v_mov_b32_e32 v91, v159
	v_mov_b32_e32 v92, v159
	v_mov_b32_e32 v93, v159
	v_mov_b32_e32 v110, 0
	v_mov_b32_e32 v111, v159
	v_mov_b32_e32 v112, v159
	v_mov_b32_e32 v113, v159
	v_mov_b32_e32 v106, 0
	v_mov_b32_e32 v107, v159
	v_mov_b32_e32 v108, v159
	v_mov_b32_e32 v109, v159
.LBB0_928:
	s_add_i32 s0, s24, 1
	s_cmp_ge_i32 s0, s23
	s_cbranch_scc0 .Ldsa_steady
	v_mov_b32_e32 v118, 0
	s_waitcnt vmcnt(13)
	v_dot2_f32_bf16 v118, v26, v26, v118
	v_dot2_f32_bf16 v118, v27, v27, v118
	ds_write_b128 v244, v[26:29]
	v_dot2_f32_bf16 v118, v28, v28, v118
	v_dot2_f32_bf16 v118, v29, v29, v118
	ds_write_b128 v245, v[18:21]
	v_dot2_f32_bf16 v118, v18, v18, v118
	v_dot2_f32_bf16 v118, v19, v19, v118
	ds_write_b128 v246, v[22:25]
	v_dot2_f32_bf16 v118, v20, v20, v118
	v_dot2_f32_bf16 v118, v21, v21, v118
	v_dot2_f32_bf16 v118, v22, v22, v118
	s_waitcnt vmcnt(12)
	ds_write_b128 v247, v[30:33]
	v_dot2_f32_bf16 v118, v23, v23, v118
	v_dot2_f32_bf16 v118, v24, v24, v118
	v_dot2_f32_bf16 v118, v25, v25, v118
	v_dot2_f32_bf16 v118, v30, v30, v118
	v_mfma_f32_16x16x32_bf16 v[114:117], v[2:5], v[26:29], 0
	v_dot2_f32_bf16 v118, v31, v31, v118
	v_dot2_f32_bf16 v118, v32, v32, v118
	v_dot2_f32_bf16 v118, v33, v33, v118
	v_mfma_f32_16x16x32_bf16 v[114:117], v[6:9], v[18:21], v[114:117]
	s_nop 1
	v_mov_b32_e32 v119, v118
	s_nop 1
	v_permlane16_swap_b32_e32 v118, v119
	v_add_f32_e32 v161, v118, v119
	v_mfma_f32_16x16x32_bf16 v[114:117], v[10:13], v[22:25], v[114:117]
	ds_bpermute_b32 v172, v248, v161
	v_mfma_f32_16x16x32_bf16 v[114:117], v[14:17], v[30:33], v[114:117]
	s_nop 7
	v_cndmask_b32_e64 v114, v114, v115, s[66:67]
	v_cndmask_b32_e64 v114, v114, v116, s[40:41]
	v_cndmask_b32_e64 v114, v114, v117, s[68:69]
	s_nop 1
	v_mov_b32_e32 v115, 0
	s_waitcnt vmcnt(9)
	v_dot2_f32_bf16 v115, v42, v42, v115
	v_mfma_f32_16x16x32_bf16 v[116:119], v[2:5], v[42:45], 0
	v_dot2_f32_bf16 v115, v43, v43, v115
	v_dot2_f32_bf16 v115, v44, v44, v115
	ds_write_b128 v244, v[42:45] offset:4096
	v_dot2_f32_bf16 v115, v45, v45, v115
	v_dot2_f32_bf16 v115, v34, v34, v115
	ds_write_b128 v245, v[34:37] offset:4096
	v_dot2_f32_bf16 v115, v35, v35, v115
	v_dot2_f32_bf16 v115, v36, v36, v115
	v_mfma_f32_16x16x32_bf16 v[116:119], v[6:9], v[34:37], v[116:119]
	v_dot2_f32_bf16 v115, v37, v37, v115
	ds_write_b128 v246, v[38:41] offset:4096
	v_dot2_f32_bf16 v115, v38, v38, v115
	v_dot2_f32_bf16 v115, v39, v39, v115
	s_waitcnt vmcnt(8)
	ds_write_b128 v247, v[46:49] offset:4096
	v_dot2_f32_bf16 v115, v40, v40, v115
	v_mfma_f32_16x16x32_bf16 v[116:119], v[10:13], v[38:41], v[116:119]
	v_dot2_f32_bf16 v115, v41, v41, v115
	v_dot2_f32_bf16 v115, v46, v46, v115
	v_mfma_f32_16x16x32_bf16 v[116:119], v[14:17], v[46:49], v[116:119]
	v_dot2_f32_bf16 v115, v47, v47, v115
	s_nop 0
	v_dot2_f32_bf16 v115, v48, v48, v115
	s_nop 0
	v_dot2_f32_bf16 v115, v49, v49, v115
	s_nop 2
	v_mov_b32_e32 v120, v115
	s_nop 1
	v_permlane16_swap_b32_e32 v115, v120
	v_add_f32_e32 v115, v115, v120
	ds_bpermute_b32 v173, v248, v115
	v_cndmask_b32_e64 v116, v116, v117, s[66:67]
	v_cndmask_b32_e64 v116, v116, v118, s[40:41]
	v_cndmask_b32_e64 v116, v116, v119, s[68:69]
	v_mov_b32_e32 v117, 0
	s_waitcnt vmcnt(5)
; #define LAS __attribute__((address_space(3)))
;     ...
;       auto gl = [&](int b) {
; #pragma unroll
;           for (int jj = 0; jj < 4; ++jj) { const int kx = list[(b * 4 + jj) * 16 + c16] & 4095; const u16* cp = prow + (size_t)kx * NP + C_BC + quad * 8;
; #pragma unroll
;               for (int ks = 0; ks < 4; ++ks) w[jj][ks] = *(const u32x4*)(cp + ks * 32); } };
;     ...
;           for (int jj = 0; jj < 4; ++jj) {
;               const int rho = jj * 16 + c16, slot = b * 64 + rho;
;               f32x4 a = {0.f, 0.f, 0.f, 0.f}; float ss = 0.f;
; #pragma unroll
;               for (int ks = 0; ks < 4; ++ks) {
; #pragma unroll
;                   for (int e = 0; e < 4; ++e) asm("v_dot2_f32_bf16 %0, %1, %1, %0" : "+v"(ss) : "v"(w[jj][ks][e]));
;                   a = __builtin_amdgcn_mfma_f32_16x16x32_bf16(qa[ks], *reinterpret_cast<const bf16x8*>(&w[jj][ks]), a, 0, 0, 0);
;                   *(LAS u32x4*)(wbase + rho * 256 + (((ks * 4 + quad) ^ fsw) << 4)) = w[jj][ks]; }
;               ss += __shfl_xor(ss, 16); ss += __shfl_xor(ss, 32);
;               const float rstd = rsqrtf(ss * (1.f / 128.f) + EPS);
;               const float av = quad == 0 ? a[0] : (quad == 1 ? a[1] : (quad == 2 ? a[2] : a[3]));
;               rsv[jj] = rstd; lgv[jj] = (slot < kcount) ? av * rstd * 0.08838834764831845f : -__builtin_inff();
;           }
;           if (b + 1 < nb) gl(b + 1);
	v_dot2_f32_bf16 v117, v58, v58, v117
	v_mfma_f32_16x16x32_bf16 v[118:121], v[2:5], v[58:61], 0
	v_dot2_f32_bf16 v117, v59, v59, v117
	v_dot2_f32_bf16 v117, v60, v60, v117
	ds_write_b128 v244, v[58:61] offset:8192
	v_dot2_f32_bf16 v117, v61, v61, v117
	v_dot2_f32_bf16 v117, v50, v50, v117
	ds_write_b128 v245, v[50:53] offset:8192
	v_dot2_f32_bf16 v117, v51, v51, v117
	v_dot2_f32_bf16 v117, v52, v52, v117
	v_mfma_f32_16x16x32_bf16 v[118:121], v[6:9], v[50:53], v[118:121]
	v_dot2_f32_bf16 v117, v53, v53, v117
	ds_write_b128 v246, v[54:57] offset:8192
	v_dot2_f32_bf16 v117, v54, v54, v117
	v_dot2_f32_bf16 v117, v55, v55, v117
	s_waitcnt vmcnt(4)
	ds_write_b128 v247, v[62:65] offset:8192
	v_dot2_f32_bf16 v117, v56, v56, v117
	v_mfma_f32_16x16x32_bf16 v[118:121], v[10:13], v[54:57], v[118:121]
	v_dot2_f32_bf16 v117, v57, v57, v117
	v_dot2_f32_bf16 v117, v62, v62, v117
	v_mfma_f32_16x16x32_bf16 v[118:121], v[14:17], v[62:65], v[118:121]
	v_dot2_f32_bf16 v117, v63, v63, v117
	s_nop 0
	v_dot2_f32_bf16 v117, v64, v64, v117
	s_nop 0
	v_dot2_f32_bf16 v117, v65, v65, v117
	s_nop 2
	v_mov_b32_e32 v123, v117
	s_nop 1
	v_permlane16_swap_b32_e32 v117, v123
	v_add_f32_e32 v117, v117, v123
	ds_bpermute_b32 v174, v248, v117
	v_cndmask_b32_e64 v118, v118, v119, s[66:67]
	v_cndmask_b32_e64 v118, v118, v120, s[40:41]
	v_cndmask_b32_e64 v118, v118, v121, s[68:69]
	v_mov_b32_e32 v119, 0
	s_waitcnt vmcnt(1)
	v_dot2_f32_bf16 v119, v74, v74, v119
	v_mfma_f32_16x16x32_bf16 v[176:179], v[2:5], v[74:77], 0
	v_dot2_f32_bf16 v119, v75, v75, v119
	v_dot2_f32_bf16 v119, v76, v76, v119
	v_mfma_f32_16x16x32_bf16 v[176:179], v[6:9], v[66:69], v[176:179]
	v_dot2_f32_bf16 v119, v77, v77, v119
	ds_write_b128 v244, v[74:77] offset:12288
	v_dot2_f32_bf16 v119, v66, v66, v119
	v_mfma_f32_16x16x32_bf16 v[176:179], v[10:13], v[70:73], v[176:179]
	v_dot2_f32_bf16 v119, v67, v67, v119
	v_dot2_f32_bf16 v119, v68, v68, v119
	ds_write_b128 v245, v[66:69] offset:12288
	v_dot2_f32_bf16 v119, v69, v69, v119
	v_dot2_f32_bf16 v119, v70, v70, v119
	ds_write_b128 v246, v[70:73] offset:12288
	v_dot2_f32_bf16 v119, v71, v71, v119
	v_cmp_lt_i32_e32 vcc, 0, v128
	v_dot2_f32_bf16 v119, v72, v72, v119
	s_nop 0
	v_dot2_f32_bf16 v119, v73, v73, v119
	s_waitcnt vmcnt(0)
	v_dot2_f32_bf16 v119, v78, v78, v119
	s_nop 0
	v_dot2_f32_bf16 v119, v79, v79, v119
	s_nop 0
	v_dot2_f32_bf16 v119, v80, v80, v119
	s_nop 0
	v_dot2_f32_bf16 v119, v81, v81, v119
	s_nop 2
	v_mov_b32_e32 v0, v119
	s_nop 1
	v_permlane16_swap_b32_e32 v119, v0
	v_add_f32_e32 v119, v119, v0
	ds_bpermute_b32 v175, v248, v119
	v_mfma_f32_16x16x32_bf16 v[120:123], v[14:17], v[78:81], v[176:179]
	ds_write_b128 v247, v[78:81] offset:12288
	s_nop 5
	v_cndmask_b32_e64 v120, v120, v121, s[66:67]
	v_cndmask_b32_e64 v120, v120, v122, s[40:41]
	v_cndmask_b32_e64 v120, v120, v123, s[68:69]
	s_add_i32 s24, s24, 1
	s_cmp_ge_i32 s24, s23
	s_cbranch_scc1 .LBB0_946
	ds_read_u16 v0, v154
	ds_read_u16 v18, v154 offset:32
	ds_read_u16 v50, v154 offset:64
	ds_read_u16 v51, v154 offset:96
	s_mov_b32 s1, 0x5040100
	s_movk_i32 s20, 0xfff
	s_waitcnt lgkmcnt(2)
	v_perm_b32 v0, v18, v0, s1
	v_and_b32_e32 v18, 0xfff0fff, v0
	v_bitop3_b32 v0, v0, s20, v207 bitop3:0x80
	v_mul_u32_u24_e32 v0, 0x5800, v0
	v_mul_u32_u24_sdwa v34, v18, s33 dst_sel:DWORD dst_unused:UNUSED_PAD src0_sel:WORD_1 src1_sel:DWORD
	v_lshl_add_u64 v[18:19], s[54:55], 0, v[0:1]
	v_mov_b32_e32 v125, v1
	v_lshl_add_u64 v[18:19], v[18:19], 0, v[124:125]
	s_movk_i32 s0, 0x1000
	v_mov_b32_e32 v35, v1
	s_waitcnt lgkmcnt(0)
	v_perm_b32 v0, v51, v50, s1
	v_add_co_u32_e32 v26, vcc, s0, v18
	v_lshl_add_u64 v[34:35], s[54:55], 0, v[34:35]
	v_and_b32_e32 v50, 0xfff0fff, v0
	v_bitop3_b32 v0, v0, s20, v207 bitop3:0x80
	v_addc_co_u32_e32 v27, vcc, 0, v19, vcc
	v_lshl_add_u64 v[34:35], v[34:35], 0, v[124:125]
	v_mul_u32_u24_e32 v0, 0x5800, v0
	v_add_co_u32_e32 v42, vcc, s0, v34
	v_mul_u32_u24_sdwa v66, v50, s33 dst_sel:DWORD dst_unused:UNUSED_PAD src0_sel:WORD_1 src1_sel:DWORD
	v_lshl_add_u64 v[50:51], s[54:55], 0, v[0:1]
	v_addc_co_u32_e32 v43, vcc, 0, v35, vcc
	v_lshl_add_u64 v[50:51], v[50:51], 0, v[124:125]
	v_mov_b32_e32 v67, v1
	v_add_co_u32_e32 v58, vcc, s0, v50
	v_lshl_add_u64 v[66:67], s[54:55], 0, v[66:67]
	s_nop 0
	v_addc_co_u32_e32 v59, vcc, 0, v51, vcc
	v_lshl_add_u64 v[66:67], v[66:67], 0, v[124:125]
	s_mov_b64 s[26:27], 0x1000
	v_add_co_u32_e32 v74, vcc, 0x1000, v66
	v_lshl_add_u64 v[30:31], v[18:19], 0, s[26:27]
	v_lshl_add_u64 v[46:47], v[34:35], 0, s[26:27]
	v_lshl_add_u64 v[62:63], v[50:51], 0, s[26:27]
	v_lshl_add_u64 v[78:79], v[66:67], 0, s[26:27]
	v_addc_co_u32_e32 v75, vcc, 0, v67, vcc
	global_load_dwordx4 v[18:21], v[30:31], off offset:64
	global_load_dwordx4 v[22:25], v[30:31], off offset:128
	s_nop 0
	global_load_dwordx4 v[26:29], v[26:27], off
	s_nop 0
	global_load_dwordx4 v[30:33], v[30:31], off offset:192
	s_nop 0
	global_load_dwordx4 v[34:37], v[46:47], off offset:64
	global_load_dwordx4 v[38:41], v[46:47], off offset:128
	s_nop 0
	global_load_dwordx4 v[42:45], v[42:43], off
	s_nop 0
	global_load_dwordx4 v[46:49], v[46:47], off offset:192
	s_nop 0
	global_load_dwordx4 v[50:53], v[62:63], off offset:64
	global_load_dwordx4 v[54:57], v[62:63], off offset:128
	s_nop 0
	global_load_dwordx4 v[58:61], v[58:59], off
	s_nop 0
	global_load_dwordx4 v[62:65], v[62:63], off offset:192
	s_nop 0
	global_load_dwordx4 v[66:69], v[78:79], off offset:64
	global_load_dwordx4 v[70:73], v[78:79], off offset:128
	s_nop 0
	global_load_dwordx4 v[74:77], v[74:75], off
	s_nop 0
	global_load_dwordx4 v[78:81], v[78:79], off offset:192

; #define LAS __attribute__((address_space(3)))
;     ...
;       auto gl = [&](int b) {
; #pragma unroll
;           for (int jj = 0; jj < 4; ++jj) { const int kx = list[(b * 4 + jj) * 16 + c16] & 4095; const u16* cp = prow + (size_t)kx * NP + C_BC + quad * 8;
; #pragma unroll
;               for (int ks = 0; ks < 4; ++ks) w[jj][ks] = *(const u32x4*)(cp + ks * 32); } };
;       if (nb > 0) gl(0);
;       for (int b = 0; b < nb; ++b) {
;           float lgv[4], rsv[4];
; #pragma unroll
;           for (int jj = 0; jj < 4; ++jj) {
;               const int rho = jj * 16 + c16, slot = b * 64 + rho;
;               f32x4 a = {0.f, 0.f, 0.f, 0.f}; float ss = 0.f;
; #pragma unroll
;               for (int ks = 0; ks < 4; ++ks) {
; #pragma unroll
;                   for (int e = 0; e < 4; ++e) asm("v_dot2_f32_bf16 %0, %1, %1, %0" : "+v"(ss) : "v"(w[jj][ks][e]));
;                   a = __builtin_amdgcn_mfma_f32_16x16x32_bf16(qa[ks], *reinterpret_cast<const bf16x8*>(&w[jj][ks]), a, 0, 0, 0);
;                   *(LAS u32x4*)(wbase + rho * 256 + (((ks * 4 + quad) ^ fsw) << 4)) = w[jj][ks]; }
;               ss += __shfl_xor(ss, 16); ss += __shfl_xor(ss, 32);
;               const float rstd = rsqrtf(ss * (1.f / 128.f) + EPS);
;               const float av = quad == 0 ? a[0] : (quad == 1 ? a[1] : (quad == 2 ? a[2] : a[3]));
;               rsv[jj] = rstd; lgv[jj] = (slot < kcount) ? av * rstd * 0.08838834764831845f : -__builtin_inff();
;           }
;           if (b + 1 < nb) gl(b + 1);
.Ldsa_steady:
	ds_read_u16 v232, v154
	ds_read_u16 v234, v154 offset:32
	ds_read_u16 v236, v154 offset:64
	ds_read_u16 v238, v154 offset:96
	v_mov_b32_e32 v240, v124
	v_mov_b32_e32 v241, 0
	v_mov_b32_e32 v233, 0
	v_mov_b32_e32 v235, 0
	v_mov_b32_e32 v237, 0
	v_mov_b32_e32 v239, 0
	s_mov_b64 s[0:1], 0x1000
	v_lshl_add_u64 v[242:243], s[54:55], 0, v[240:241]
	v_lshl_add_u64 v[242:243], v[242:243], 0, s[0:1]
	s_waitcnt lgkmcnt(0)
	v_and_b32_e32 v232, 0xfff, v232
	v_mul_u32_u24_e32 v232, 0x5800, v232
	v_lshl_add_u64 v[224:225], v[232:233], 0, v[242:243]
	v_and_b32_e32 v234, 0xfff, v234
	v_mul_u32_u24_e32 v234, 0x5800, v234
	v_lshl_add_u64 v[226:227], v[234:235], 0, v[242:243]
	v_and_b32_e32 v236, 0xfff, v236
	v_mul_u32_u24_e32 v236, 0x5800, v236
	v_lshl_add_u64 v[228:229], v[236:237], 0, v[242:243]
	v_and_b32_e32 v238, 0xfff, v238
	v_mul_u32_u24_e32 v238, 0x5800, v238
	v_lshl_add_u64 v[230:231], v[238:239], 0, v[242:243]
	v_mov_b32_e32 v118, 0
	s_waitcnt vmcnt(13)
	v_dot2_f32_bf16 v118, v26, v26, v118
	v_dot2_f32_bf16 v118, v27, v27, v118
	ds_write_b128 v244, v[26:29]
	v_dot2_f32_bf16 v118, v28, v28, v118
	v_dot2_f32_bf16 v118, v29, v29, v118
	ds_write_b128 v245, v[18:21]
	v_dot2_f32_bf16 v118, v18, v18, v118
	v_dot2_f32_bf16 v118, v19, v19, v118
	ds_write_b128 v246, v[22:25]
	v_dot2_f32_bf16 v118, v20, v20, v118
	v_dot2_f32_bf16 v118, v21, v21, v118
	v_dot2_f32_bf16 v118, v22, v22, v118
	s_waitcnt vmcnt(12)
	ds_write_b128 v247, v[30:33]
	v_dot2_f32_bf16 v118, v23, v23, v118
	v_dot2_f32_bf16 v118, v24, v24, v118
	v_dot2_f32_bf16 v118, v25, v25, v118
	v_dot2_f32_bf16 v118, v30, v30, v118
	v_mfma_f32_16x16x32_bf16 v[114:117], v[2:5], v[26:29], 0
	v_dot2_f32_bf16 v118, v31, v31, v118
	v_dot2_f32_bf16 v118, v32, v32, v118
	v_dot2_f32_bf16 v118, v33, v33, v118
	v_mfma_f32_16x16x32_bf16 v[114:117], v[6:9], v[18:21], v[114:117]
	s_nop 1
	v_mov_b32_e32 v119, v118
	s_nop 1
	v_permlane16_swap_b32_e32 v118, v119
	v_add_f32_e32 v161, v118, v119
	v_mfma_f32_16x16x32_bf16 v[114:117], v[10:13], v[22:25], v[114:117]
	ds_bpermute_b32 v172, v248, v161
	v_mfma_f32_16x16x32_bf16 v[114:117], v[14:17], v[30:33], v[114:117]
	global_load_dwordx4 v[18:21], v[224:225], off offset:64
	global_load_dwordx4 v[22:25], v[224:225], off offset:128
	global_load_dwordx4 v[26:29], v[224:225], off
	global_load_dwordx4 v[30:33], v[224:225], off offset:192
	s_nop 3
	v_cndmask_b32_e64 v114, v114, v115, s[66:67]
	v_cndmask_b32_e64 v114, v114, v116, s[40:41]
	v_cndmask_b32_e64 v114, v114, v117, s[68:69]
	s_nop 1
	v_mov_b32_e32 v115, 0
	s_waitcnt vmcnt(13)
	v_dot2_f32_bf16 v115, v42, v42, v115
	v_mfma_f32_16x16x32_bf16 v[116:119], v[2:5], v[42:45], 0
	v_dot2_f32_bf16 v115, v43, v43, v115
	v_dot2_f32_bf16 v115, v44, v44, v115
	ds_write_b128 v244, v[42:45] offset:4096
	v_dot2_f32_bf16 v115, v45, v45, v115
	v_dot2_f32_bf16 v115, v34, v34, v115
	ds_write_b128 v245, v[34:37] offset:4096
	v_dot2_f32_bf16 v115, v35, v35, v115
	v_dot2_f32_bf16 v115, v36, v36, v115
	v_mfma_f32_16x16x32_bf16 v[116:119], v[6:9], v[34:37], v[116:119]
	v_dot2_f32_bf16 v115, v37, v37, v115
	ds_write_b128 v246, v[38:41] offset:4096
	v_dot2_f32_bf16 v115, v38, v38, v115
	v_dot2_f32_bf16 v115, v39, v39, v115
	s_waitcnt vmcnt(12)
	ds_write_b128 v247, v[46:49] offset:4096
	v_dot2_f32_bf16 v115, v40, v40, v115
	v_mfma_f32_16x16x32_bf16 v[116:119], v[10:13], v[38:41], v[116:119]
	v_dot2_f32_bf16 v115, v41, v41, v115
	v_dot2_f32_bf16 v115, v46, v46, v115
	v_mfma_f32_16x16x32_bf16 v[116:119], v[14:17], v[46:49], v[116:119]
	v_dot2_f32_bf16 v115, v47, v47, v115
	s_nop 0
	v_dot2_f32_bf16 v115, v48, v48, v115
	s_nop 0
	v_dot2_f32_bf16 v115, v49, v49, v115
	global_load_dwordx4 v[34:37], v[226:227], off offset:64
	global_load_dwordx4 v[38:41], v[226:227], off offset:128
	global_load_dwordx4 v[42:45], v[226:227], off
	global_load_dwordx4 v[46:49], v[226:227], off offset:192
	s_nop 2
	v_mov_b32_e32 v120, v115
	s_nop 1
	v_permlane16_swap_b32_e32 v115, v120
	v_add_f32_e32 v115, v115, v120
	ds_bpermute_b32 v173, v248, v115
	v_cndmask_b32_e64 v116, v116, v117, s[66:67]
	v_cndmask_b32_e64 v116, v116, v118, s[40:41]
	v_cndmask_b32_e64 v116, v116, v119, s[68:69]
	v_mov_b32_e32 v117, 0
	s_waitcnt vmcnt(13)
; #define LAS __attribute__((address_space(3)))
;     ...
;           for (int jj = 0; jj < 4; ++jj) {
;               const int rho = jj * 16 + c16, slot = b * 64 + rho;
;               f32x4 a = {0.f, 0.f, 0.f, 0.f}; float ss = 0.f;
; #pragma unroll
;               for (int ks = 0; ks < 4; ++ks) {
; #pragma unroll
;                   for (int e = 0; e < 4; ++e) asm("v_dot2_f32_bf16 %0, %1, %1, %0" : "+v"(ss) : "v"(w[jj][ks][e]));
;                   a = __builtin_amdgcn_mfma_f32_16x16x32_bf16(qa[ks], *reinterpret_cast<const bf16x8*>(&w[jj][ks]), a, 0, 0, 0);
;                   *(LAS u32x4*)(wbase + rho * 256 + (((ks * 4 + quad) ^ fsw) << 4)) = w[jj][ks]; }
;               ss += __shfl_xor(ss, 16); ss += __shfl_xor(ss, 32);
;               const float rstd = rsqrtf(ss * (1.f / 128.f) + EPS);
;               const float av = quad == 0 ? a[0] : (quad == 1 ? a[1] : (quad == 2 ? a[2] : a[3]));
;               rsv[jj] = rstd; lgv[jj] = (slot < kcount) ? av * rstd * 0.08838834764831845f : -__builtin_inff();
;           }
;           if (b + 1 < nb) gl(b + 1);
	v_dot2_f32_bf16 v117, v58, v58, v117
	v_mfma_f32_16x16x32_bf16 v[118:121], v[2:5], v[58:61], 0
	v_dot2_f32_bf16 v117, v59, v59, v117
	v_dot2_f32_bf16 v117, v60, v60, v117
	ds_write_b128 v244, v[58:61] offset:8192
	v_dot2_f32_bf16 v117, v61, v61, v117
	v_dot2_f32_bf16 v117, v50, v50, v117
	ds_write_b128 v245, v[50:53] offset:8192
	v_dot2_f32_bf16 v117, v51, v51, v117
	v_dot2_f32_bf16 v117, v52, v52, v117
	v_mfma_f32_16x16x32_bf16 v[118:121], v[6:9], v[50:53], v[118:121]
	v_dot2_f32_bf16 v117, v53, v53, v117
	ds_write_b128 v246, v[54:57] offset:8192
	v_dot2_f32_bf16 v117, v54, v54, v117
	v_dot2_f32_bf16 v117, v55, v55, v117
	s_waitcnt vmcnt(12)
	ds_write_b128 v247, v[62:65] offset:8192
	v_dot2_f32_bf16 v117, v56, v56, v117
	v_mfma_f32_16x16x32_bf16 v[118:121], v[10:13], v[54:57], v[118:121]
	v_dot2_f32_bf16 v117, v57, v57, v117
	v_dot2_f32_bf16 v117, v62, v62, v117
	v_mfma_f32_16x16x32_bf16 v[118:121], v[14:17], v[62:65], v[118:121]
	v_dot2_f32_bf16 v117, v63, v63, v117
	s_nop 0
	v_dot2_f32_bf16 v117, v64, v64, v117
	s_nop 0
	v_dot2_f32_bf16 v117, v65, v65, v117
	global_load_dwordx4 v[50:53], v[228:229], off offset:64
	global_load_dwordx4 v[54:57], v[228:229], off offset:128
	global_load_dwordx4 v[58:61], v[228:229], off
	global_load_dwordx4 v[62:65], v[228:229], off offset:192
	s_nop 2
	v_mov_b32_e32 v123, v117
	s_nop 1
	v_permlane16_swap_b32_e32 v117, v123
	v_add_f32_e32 v117, v117, v123
	ds_bpermute_b32 v174, v248, v117
	v_cndmask_b32_e64 v118, v118, v119, s[66:67]
	v_cndmask_b32_e64 v118, v118, v120, s[40:41]
	v_cndmask_b32_e64 v118, v118, v121, s[68:69]
	v_mov_b32_e32 v119, 0
	s_waitcnt vmcnt(13)
	v_dot2_f32_bf16 v119, v74, v74, v119
	v_mfma_f32_16x16x32_bf16 v[176:179], v[2:5], v[74:77], 0
	v_dot2_f32_bf16 v119, v75, v75, v119
	v_dot2_f32_bf16 v119, v76, v76, v119
	v_mfma_f32_16x16x32_bf16 v[176:179], v[6:9], v[66:69], v[176:179]
	v_dot2_f32_bf16 v119, v77, v77, v119
	ds_write_b128 v244, v[74:77] offset:12288
	v_dot2_f32_bf16 v119, v66, v66, v119
	v_mfma_f32_16x16x32_bf16 v[176:179], v[10:13], v[70:73], v[176:179]
	v_dot2_f32_bf16 v119, v67, v67, v119
	v_dot2_f32_bf16 v119, v68, v68, v119
	ds_write_b128 v245, v[66:69] offset:12288
	v_dot2_f32_bf16 v119, v69, v69, v119
	v_dot2_f32_bf16 v119, v70, v70, v119
	ds_write_b128 v246, v[70:73] offset:12288
	v_dot2_f32_bf16 v119, v71, v71, v119
	v_cmp_lt_i32_e32 vcc, 0, v128
	v_dot2_f32_bf16 v119, v72, v72, v119
	s_nop 0
	v_dot2_f32_bf16 v119, v73, v73, v119
	s_waitcnt vmcnt(12)
	v_dot2_f32_bf16 v119, v78, v78, v119
	s_nop 0
	v_dot2_f32_bf16 v119, v79, v79, v119
	s_nop 0
	v_dot2_f32_bf16 v119, v80, v80, v119
	s_nop 0
	v_dot2_f32_bf16 v119, v81, v81, v119
	s_nop 2
	v_mov_b32_e32 v0, v119
	s_nop 1
	v_permlane16_swap_b32_e32 v119, v0
	v_add_f32_e32 v119, v119, v0
	ds_bpermute_b32 v175, v248, v119
	v_mfma_f32_16x16x32_bf16 v[120:123], v[14:17], v[78:81], v[176:179]
	ds_write_b128 v247, v[78:81] offset:12288
	global_load_dwordx4 v[66:69], v[230:231], off offset:64
	global_load_dwordx4 v[70:73], v[230:231], off offset:128
	global_load_dwordx4 v[74:77], v[230:231], off
	global_load_dwordx4 v[78:81], v[230:231], off offset:192
	s_nop 1
	v_cndmask_b32_e64 v120, v120, v121, s[66:67]
	v_cndmask_b32_e64 v120, v120, v122, s[40:41]
	v_cndmask_b32_e64 v120, v120, v123, s[68:69]
	s_add_i32 s24, s24, 1
	s_branch .LBB0_946
